# attn_item: K/V prefetch issued one iteration ahead (after mid barrier), LDS staging write moved to top of first half
# speedup vs baseline: 1.0333x; 1.0160x over previous
; __device__ __forceinline__ float bflo(unsigned u) { return __uint_as_float(u << 16); }
; __device__ __forceinline__ float bfhi(unsigned u) { return __uint_as_float(u & 0xffff0000u); }
; __device__ __forceinline__ void rope_cs(int pos, int i, float& c, float& s) {
;     const double rev = (double)pos * INVF[i] * 0.15915494309189535;
;     const float fr = (float)(rev - floor(rev));
;     c = __builtin_amdgcn_cosf(fr); s = __builtin_amdgcn_sinf(fr);
; __device__ __forceinline__ void q_prologue(const Params& p, int l, int qrow, int pos, int h, int hf, int lane, bf16x8 (&qf)[6]) {
;     ...
;     const bf16_t* qp = qraw + (size_t)qrow * 768 + h * DQK + 8 * hf;
;     float v[6][8];
; #pragma unroll
;     for (int s = 0; s < 6; ++s) { const u32x4 raw = *(const u32x4*)(qp + 16 * s);
;         v[s][0] = bflo(raw.x); v[s][1] = bfhi(raw.x); v[s][2] = bflo(raw.y); v[s][3] = bfhi(raw.y); v[s][4] = bflo(raw.z); v[s][5] = bfhi(raw.z); v[s][6] = bflo(raw.w); v[s][7] = bfhi(raw.w); }
; #pragma unroll
;     for (int e = 0; e < 8; ++e) { float c, s; rope_cs(pos, 8 * hf + e, c, s); const float x1 = v[4][e], x2 = v[5][e]; v[4][e] = x1 * c - x2 * s; v[5][e] = x1 * s + x2 * c; }
.LBB0_610:
	s_or_b64 exec, exec, s[48:49]
	s_bitcmp0_b32 s9, 0
	s_cselect_b32 s5, s16, s17
	s_ashr_i32 s10, s10, 6
	s_lshl_b32 s11, s5, 3
	s_movk_i32 s12, 0xd0
	v_and_b32_e32 v52, 63, v136
	v_and_b32_e32 v59, 31, v136
	v_bfe_u32 v246, v136, 5, 1
	s_add_i32 s10, s11, s10
	v_mad_u64_u32 v[234:235], s[12:13], v56, s12, v[0:1]
	v_mul_u32_u24_e32 v139, 0xd0, v138
	s_lshl_b32 s11, s10, 5
	v_add_u32_e32 v2, 16, v59
	s_add_i32 s12, s11, s20
	v_add_u32_e32 v232, s12, v2
	v_add_u32_e32 v26, s11, v2
	v_mov_b64_e32 v[2:3], s[24:25]
	s_movk_i32 s11, 0x600
	v_mad_i64_i32 v[2:3], s[12:13], v232, s11, v[2:3]
	v_lshlrev_b32_e32 v236, 4, v246
	v_mov_b32_e32 v237, v1
	v_lshl_add_u64 v[18:19], v[2:3], 0, v[236:237]
	v_lshlrev_b32_e32 v36, 6, v246
	s_getpc_b64 s[12:13]
	s_add_u32 s12, s12, _ZL4INVF@rel32@lo+4
	s_addc_u32 s13, s13, _ZL4INVF@rel32@hi+12
	global_load_dwordx4 v[2:5], v[18:19], off
	global_load_dwordx4 v[6:9], v[18:19], off offset:32
	global_load_dwordx4 v[10:13], v[18:19], off offset:64
	global_load_dwordx4 v[14:17], v[18:19], off offset:96
	global_load_dwordx4 v[22:25], v[18:19], off offset:128
	s_nop 0
	global_load_dwordx4 v[18:21], v[18:19], off offset:160
	v_cvt_f64_i32_e32 v[34:35], v26
	global_load_dwordx4 v[26:29], v36, s[12:13] offset:48
	global_load_dwordx4 v[30:33], v36, s[12:13] offset:32
	global_load_dwordx4 v[42:45], v36, s[12:13] offset:16
	global_load_dwordx4 v[38:41], v36, s[12:13]
	v_and_b32_e32 v126, 32, v136
	s_movk_i32 s11, 0x90
	v_mad_u64_u32 v[238:239], s[12:13], v56, s11, v[0:1]
	v_add_u32_e32 v0, 0, v238
	s_waitcnt vmcnt(9)
	v_lshlrev_b32_e32 v128, 16, v2
	s_waitcnt vmcnt(8)
	v_lshlrev_b32_e32 v92, 16, v9
	s_waitcnt vmcnt(7)
	v_lshlrev_b32_e32 v84, 16, v13
	s_waitcnt vmcnt(6)
	v_lshlrev_b32_e32 v82, 16, v14
	s_waitcnt vmcnt(3)
	v_mul_f64 v[26:27], v[26:27], v[34:35]
	s_waitcnt vmcnt(2)
	v_mul_f64 v[30:31], v[30:31], v[34:35]
	s_waitcnt vmcnt(1)
	v_mul_f64 v[44:45], v[44:45], v[34:35]
	s_waitcnt vmcnt(0)
	v_mul_f64 v[40:41], v[40:41], v[34:35]
	v_mul_f64 v[36:37], v[38:39], v[34:35]
	v_mul_f64 v[46:47], v[40:41], s[22:23]
	v_mul_f64 v[38:39], v[36:37], s[22:23]
	v_floor_f64_e32 v[46:47], v[46:47]
	v_floor_f64_e32 v[38:39], v[38:39]
	v_fma_f64 v[40:41], v[40:41], s[22:23], -v[46:47]
	v_fma_f64 v[36:37], v[36:37], s[22:23], -v[38:39]
	v_cvt_f32_f64_e32 v39, v[40:41]
	v_mul_f64 v[40:41], v[42:43], v[34:35]
	v_mul_f64 v[46:47], v[44:45], s[22:23]
	v_mul_f64 v[42:43], v[40:41], s[22:23]
	v_floor_f64_e32 v[46:47], v[46:47]
	v_floor_f64_e32 v[42:43], v[42:43]
	v_fma_f64 v[44:45], v[44:45], s[22:23], -v[46:47]
	v_fma_f64 v[40:41], v[40:41], s[22:23], -v[42:43]
	v_cvt_f32_f64_e32 v43, v[44:45]
	v_mul_f64 v[44:45], v[30:31], s[22:23]
	v_floor_f64_e32 v[44:45], v[44:45]
	v_fma_f64 v[30:31], v[30:31], s[22:23], -v[44:45]
	v_cvt_f32_f64_e32 v30, v[30:31]
	v_cos_f32_e32 v44, v30
	v_sin_f32_e32 v46, v30
	v_mul_f64 v[30:31], v[32:33], v[34:35]
	v_mul_f64 v[32:33], v[30:31], s[22:23]
	v_floor_f64_e32 v[32:33], v[32:33]
	v_fma_f64 v[30:31], v[30:31], s[22:23], -v[32:33]
	v_cvt_f32_f64_e32 v30, v[30:31]
	v_cos_f32_e32 v45, v30
	v_sin_f32_e32 v47, v30
	v_mul_f64 v[30:31], v[26:27], s[22:23]
	v_floor_f64_e32 v[30:31], v[30:31]
	v_fma_f64 v[26:27], v[26:27], s[22:23], -v[30:31]
	v_cvt_f32_f64_e32 v26, v[26:27]
	v_cos_f32_e32 v48, v26
	v_sin_f32_e32 v50, v26
	v_mul_f64 v[26:27], v[28:29], v[34:35]
	v_mul_f64 v[28:29], v[26:27], s[22:23]
	v_floor_f64_e32 v[28:29], v[28:29]
	v_fma_f64 v[26:27], v[26:27], s[22:23], -v[28:29]
	v_cvt_f32_f64_e32 v37, v[36:37]
	v_cvt_f32_f64_e32 v41, v[40:41]
	v_cvt_f32_f64_e32 v26, v[26:27]
	v_cos_f32_e32 v36, v37
	v_sin_f32_e32 v38, v37
	v_cos_f32_e32 v37, v39
	v_cos_f32_e32 v40, v41
	v_sin_f32_e32 v42, v41
	v_cos_f32_e32 v41, v43
	v_cos_f32_e32 v49, v26
	v_sin_f32_e32 v39, v39
	v_sin_f32_e32 v43, v43
	v_sin_f32_e32 v51, v26
	v_lshlrev_b32_e32 v72, 16, v20
	v_and_b32_e32 v73, 0xffff0000, v20
	v_lshlrev_b32_e32 v26, 2, v52
	v_lshlrev_b32_e32 v54, 16, v21
	v_and_b32_e32 v55, 0xffff0000, v21
	v_lshlrev_b32_e32 v70, 16, v24
	v_and_b32_e32 v71, 0xffff0000, v24
	v_pk_mul_f32 v[20:21], v[44:45], v[72:73]
	v_lshlrev_b32_e32 v76, 16, v19
	v_and_b32_e32 v77, 0xffff0000, v19
	v_lshlrev_b32_e32 v80, 16, v18
	v_and_b32_e32 v81, 0xffff0000, v18
	v_xor_b32_e32 v235, 0x80, v26
	v_lshlrev_b32_e32 v52, 16, v25
	v_and_b32_e32 v53, 0xffff0000, v25
	v_pk_mul_f32 v[26:27], v[48:49], v[54:55]
	v_pk_fma_f32 v[62:63], v[46:47], v[70:71], v[20:21]
	v_lshlrev_b32_e32 v74, 16, v23
	v_and_b32_e32 v75, 0xffff0000, v23
	v_pk_mul_f32 v[20:21], v[40:41], v[76:77]
	v_lshlrev_b32_e32 v78, 16, v22
	v_and_b32_e32 v79, 0xffff0000, v22
	v_pk_mul_f32 v[18:19], v[36:37], v[80:81]
	v_pk_fma_f32 v[60:61], v[50:51], v[52:53], v[26:27]
	v_pk_fma_f32 v[64:65], v[42:43], v[74:75], v[20:21]
	v_pk_fma_f32 v[22:23], v[38:39], v[78:79], v[18:19]
	v_pk_mul_f32 v[50:51], v[50:51], v[54:55]
	v_pk_mul_f32 v[46:47], v[46:47], v[72:73]
	v_pk_mul_f32 v[42:43], v[42:43], v[76:77]
	v_pk_mul_f32 v[38:39], v[38:39], v[80:81]
	global_load_dwordx4 v[24:27], v126, s[30:31] offset:336
	global_load_dwordx4 v[28:31], v126, s[30:31] offset:320
	global_load_dwordx4 v[18:21], v126, s[30:31] offset:272
	global_load_dwordx4 v[32:35], v126, s[30:31] offset:256
	v_pk_fma_f32 v[68:69], v[48:49], v[52:53], v[50:51] neg_lo:[0,0,1] neg_hi:[0,0,1]
	v_pk_fma_f32 v[70:71], v[44:45], v[70:71], v[46:47] neg_lo:[0,0,1] neg_hi:[0,0,1]
	v_pk_fma_f32 v[72:73], v[40:41], v[74:75], v[42:43] neg_lo:[0,0,1] neg_hi:[0,0,1]
	v_pk_fma_f32 v[74:75], v[36:37], v[78:79], v[38:39] neg_lo:[0,0,1] neg_hi:[0,0,1]
	v_lshlrev_b32_e32 v76, 16, v17
	v_and_b32_e32 v77, 0xffff0000, v17
	global_load_dwordx4 v[36:39], v126, s[30:31] offset:208
; #define LAS __attribute__((address_space(3)))
; __device__ __forceinline__ float shx32(float v, int lane) { return __int_as_float(__builtin_amdgcn_ds_bpermute((lane ^ 32) << 2, __float_as_int(v))); }
; __device__ __forceinline__ void q_prologue(const Params& p, int l, int qrow, int pos, int h, int hf, int lane, bf16x8 (&qf)[6]) {
;     ...
;     float ss = 0.f;
; #pragma unroll
;     for (int s = 0; s < 6; ++s)
; #pragma unroll
;         for (int e = 0; e < 8; ++e) ss += v[s][e] * v[s][e];
;     ss += shx32(ss, lane);
;     const float rs = rsqrtf(ss * (1.f / DQK) + EPS) * 0.14724444602590306f;
; __device__ __forceinline__ void attn_item(const Params& p, int l, LAS unsigned char* lds, int b, int h, int J) {
;     ...
;     u32x4 skn = *(const u32x4*)gkn, svt = *(const u32x4*)gvt, skr = {0u, 0u, 0u, 0u};
;     if (has_kr) skr = *(const u32x4*)gkr;
;     __builtin_amdgcn_sched_barrier(0);
;     bf16x8 qf[6];
;     q_prologue(p, l, qrow0 + r, NMETA + 32 * i + r, h, hf, lane, qf);
;     *(LAS u32x4*)(lds + wkn) = skn; *(LAS u32x4*)(lds + wvt) = svt; if (has_kr) *(LAS u32x4*)(lds + wkr) = skr;
;     __syncthreads();
	global_load_dwordx4 v[40:43], v126, s[30:31] offset:192
	v_lshlrev_b32_e32 v78, 16, v16
	v_and_b32_e32 v79, 0xffff0000, v16
	v_lshlrev_b32_e32 v80, 16, v15
	v_and_b32_e32 v81, 0xffff0000, v15
	v_and_b32_e32 v83, 0xffff0000, v14
	v_and_b32_e32 v85, 0xffff0000, v13
	global_load_dwordx4 v[14:17], v126, s[30:31] offset:144
	global_load_dwordx4 v[44:47], v126, s[30:31] offset:128
	v_lshlrev_b32_e32 v86, 16, v12
	v_and_b32_e32 v87, 0xffff0000, v12
	v_lshlrev_b32_e32 v88, 16, v11
	v_and_b32_e32 v89, 0xffff0000, v11
	v_lshlrev_b32_e32 v90, 16, v10
	v_and_b32_e32 v91, 0xffff0000, v10
	v_and_b32_e32 v93, 0xffff0000, v9
	global_load_dwordx4 v[10:13], v126, s[30:31] offset:80
	global_load_dwordx4 v[48:51], v126, s[30:31] offset:64
	v_lshlrev_b32_e32 v96, 16, v8
	v_and_b32_e32 v97, 0xffff0000, v8
	v_lshlrev_b32_e32 v116, 16, v7
	v_and_b32_e32 v117, 0xffff0000, v7
	v_lshlrev_b32_e32 v114, 16, v6
	v_and_b32_e32 v115, 0xffff0000, v6
	global_load_dwordx4 v[6:9], v126, s[30:31] offset:16
	global_load_dwordx4 v[52:55], v126, s[30:31]
	v_and_b32_e32 v129, 0xffff0000, v2
	v_lshlrev_b32_e32 v118, 16, v5
	v_and_b32_e32 v119, 0xffff0000, v5
	v_lshlrev_b32_e32 v126, 16, v4
	v_and_b32_e32 v127, 0xffff0000, v4
	v_lshlrev_b32_e32 v4, 16, v3
	v_and_b32_e32 v5, 0xffff0000, v3
	v_pk_mul_f32 v[2:3], v[128:129], v[128:129]
	v_pk_mul_f32 v[166:167], v[4:5], v[4:5]
	v_add_f32_e32 v2, v2, v3
	v_add_f32_e32 v2, v166, v2
	v_pk_mul_f32 v[164:165], v[126:127], v[126:127]
	v_add_f32_e32 v2, v167, v2
	v_add_f32_e32 v2, v164, v2
	v_pk_mul_f32 v[162:163], v[118:119], v[118:119]
	v_add_f32_e32 v2, v165, v2
	v_add_f32_e32 v2, v162, v2
	v_pk_mul_f32 v[160:161], v[114:115], v[114:115]
	v_add_f32_e32 v2, v163, v2
	v_add_f32_e32 v2, v160, v2
	v_pk_mul_f32 v[158:159], v[116:117], v[116:117]
	v_add_f32_e32 v2, v161, v2
	v_add_f32_e32 v2, v158, v2
	v_pk_mul_f32 v[156:157], v[96:97], v[96:97]
	v_add_f32_e32 v2, v159, v2
	v_add_f32_e32 v2, v156, v2
	v_pk_mul_f32 v[154:155], v[92:93], v[92:93]
	v_add_f32_e32 v2, v157, v2
	v_add_f32_e32 v2, v154, v2
	v_pk_mul_f32 v[152:153], v[90:91], v[90:91]
	v_add_f32_e32 v2, v155, v2
	v_add_f32_e32 v2, v152, v2
	v_pk_mul_f32 v[150:151], v[88:89], v[88:89]
	v_add_f32_e32 v2, v153, v2
	v_add_f32_e32 v2, v150, v2
	v_pk_mul_f32 v[148:149], v[86:87], v[86:87]
	v_add_f32_e32 v2, v151, v2
	v_add_f32_e32 v2, v148, v2
	v_pk_mul_f32 v[146:147], v[84:85], v[84:85]
	v_add_f32_e32 v2, v149, v2
	v_add_f32_e32 v2, v146, v2
	v_pk_mul_f32 v[144:145], v[82:83], v[82:83]
	v_add_f32_e32 v2, v147, v2
	v_add_f32_e32 v2, v144, v2
	v_pk_mul_f32 v[142:143], v[80:81], v[80:81]
	v_add_f32_e32 v2, v145, v2
	v_add_f32_e32 v2, v142, v2
	v_pk_mul_f32 v[140:141], v[78:79], v[78:79]
	v_add_f32_e32 v2, v143, v2
	v_add_f32_e32 v2, v140, v2
	v_pk_mul_f32 v[132:133], v[76:77], v[76:77]
	v_add_f32_e32 v2, v141, v2
	v_add_f32_e32 v2, v132, v2
	v_pk_mul_f32 v[130:131], v[74:75], v[74:75]
	v_add_f32_e32 v2, v133, v2
	v_add_f32_e32 v2, v130, v2
	v_pk_mul_f32 v[124:125], v[72:73], v[72:73]
	v_add_f32_e32 v2, v131, v2
	v_add_f32_e32 v2, v124, v2
	v_pk_mul_f32 v[122:123], v[70:71], v[70:71]
	v_add_f32_e32 v2, v125, v2
	v_add_f32_e32 v2, v122, v2
	v_pk_mul_f32 v[120:121], v[68:69], v[68:69]
	v_add_f32_e32 v2, v123, v2
	v_add_f32_e32 v2, v120, v2
	v_pk_mul_f32 v[112:113], v[22:23], v[22:23]
	v_add_f32_e32 v2, v121, v2
	v_add_f32_e32 v2, v112, v2
	v_pk_mul_f32 v[110:111], v[64:65], v[64:65]
	v_add_f32_e32 v2, v113, v2
	v_add_f32_e32 v2, v110, v2
	v_pk_mul_f32 v[94:95], v[62:63], v[62:63]
	v_add_f32_e32 v2, v111, v2
	v_add_f32_e32 v2, v94, v2
	v_pk_mul_f32 v[66:67], v[60:61], v[60:61]
	v_add_f32_e32 v2, v95, v2
	v_add_f32_e32 v2, v66, v2
	v_add_f32_e32 v2, v67, v2
	ds_bpermute_b32 v3, v235, v2
	v_add_u32_e32 v66, 0, v234
	ds_write_b128 v66, v[98:101]
	ds_write_b128 v0, v[102:105] offset:13312
	s_and_saveexec_b64 s[48:49], s[40:41]
	v_add3_u32 v0, v58, v139, 0
	ds_write_b128 v0, v[106:109] offset:128
	s_or_b64 exec, exec, s[48:49]
	s_cmp_lt_i32 s5, -1
	s_waitcnt lgkmcnt(0)
	s_barrier
	s_cbranch_scc1 .LBB0_606
	v_add_f32_e32 v0, v2, v3
	v_fmamk_f32 v0, v0, 0x3c2aaaab, v210
	v_mul_f32_e32 v2, 0x4b800000, v0
	v_cmp_gt_f32_e32 vcc, s95, v0
	s_movk_i32 s12, 0x70
	s_ashr_i32 s10, s10, 1
	v_cndmask_b32_e32 v0, v0, v2, vcc
	v_rsq_f32_e32 v0, v0
	s_lshl_b32 s5, s5, 2
	s_add_i32 s11, s10, 2
	s_add_i32 s5, s5, 5
	v_mul_f32_e32 v2, 0x45800000, v0
	v_cndmask_b32_e32 v0, v0, v2, vcc
	v_mul_f32_e32 v0, 0x3e16c740, v0
	v_pk_mul_f32 v[2:3], v[0:1], v[128:129] op_sel_hi:[0,1]
	s_waitcnt vmcnt(0)
; #define LAS __attribute__((address_space(3)))
; __device__ __forceinline__ unsigned pk2(float a, float b) { f32x2 v = {a, b}; bf16x2_t r = __builtin_convertvector(v, bf16x2_t); return __builtin_bit_cast(unsigned, r); }
; __device__ __forceinline__ void q_prologue(const Params& p, int l, int qrow, int pos, int h, int hf, int lane, bf16x8 (&qf)[6]) {
;     ...
; #pragma unroll
;     for (int s = 0; s < 6; ++s) { const float* g = qn + 16 * s + 8 * hf; u32x4 w;
;         w.x = pk2(v[s][0] * rs * g[0], v[s][1] * rs * g[1]); w.y = pk2(v[s][2] * rs * g[2], v[s][3] * rs * g[3]);
;         w.z = pk2(v[s][4] * rs * g[4], v[s][5] * rs * g[5]); w.w = pk2(v[s][6] * rs * g[6], v[s][7] * rs * g[7]);
;         qf[s] = __builtin_bit_cast(bf16x8, w); }
; __device__ __forceinline__ void attn_item(const Params& p, int l, LAS unsigned char* lds, int b, int h, int J) {
;     ...
;     f32x16 o0, o1;
; #pragma unroll
;     for (int q = 0; q < 16; ++q) { o0[q] = 0.f; o1[q] = 0.f; }
;     float mrun = -INFINITY, lsum = 0.f;
; #pragma nounroll
;     for (int j = 0; j < blk_nt; ++j) {
;         LAS unsigned char* cur = lds + (j & 1) * ATT_BUF; LAS unsigned char* nxt = lds + ((j + 1) & 1) * ATT_BUF;
;         const bool more = (j + 1) < blk_nt;
;         if (more) { skn = *(const u32x4*)(gkn + (size_t)(j + 1) * 64 * 512); svt = *(const u32x4*)(gvt + (size_t)(j + 1) * 512 * 64); if (has_kr) skr = *(const u32x4*)(gkr + (size_t)(j + 1) * 64 * 256); }
	v_pk_mul_f32 v[2:3], v[52:53], v[2:3]
	v_pk_mul_f32 v[4:5], v[0:1], v[4:5] op_sel_hi:[0,1]
	v_cvt_pk_bf16_f32 v110, v2, v3
	v_pk_mul_f32 v[2:3], v[0:1], v[126:127] op_sel_hi:[0,1]
	v_pk_mul_f32 v[2:3], v[6:7], v[2:3]
	v_pk_mul_f32 v[4:5], v[54:55], v[4:5]
	v_cvt_pk_bf16_f32 v112, v2, v3
	v_pk_mul_f32 v[2:3], v[0:1], v[118:119] op_sel_hi:[0,1]
	v_pk_mul_f32 v[2:3], v[8:9], v[2:3]
	v_cvt_pk_bf16_f32 v111, v4, v5
	v_cvt_pk_bf16_f32 v113, v2, v3
	v_pk_mul_f32 v[2:3], v[0:1], v[114:115] op_sel_hi:[0,1]
	v_pk_mul_f32 v[2:3], v[48:49], v[2:3]
	v_mov_b32_e32 v4, v1
	v_cvt_pk_bf16_f32 v114, v2, v3
	v_pk_mul_f32 v[2:3], v[0:1], v[116:117] op_sel_hi:[0,1]
	v_pk_mul_f32 v[2:3], v[50:51], v[2:3]
	v_mov_b32_e32 v5, v1
	v_cvt_pk_bf16_f32 v115, v2, v3
	v_pk_mul_f32 v[2:3], v[0:1], v[96:97] op_sel_hi:[0,1]
	v_pk_mul_f32 v[2:3], v[10:11], v[2:3]
	v_mov_b32_e32 v6, v1
	v_cvt_pk_bf16_f32 v116, v2, v3
	v_pk_mul_f32 v[2:3], v[0:1], v[92:93] op_sel_hi:[0,1]
	v_pk_mul_f32 v[2:3], v[12:13], v[2:3]
	v_mov_b32_e32 v7, v1
	v_cvt_pk_bf16_f32 v117, v2, v3
	v_pk_mul_f32 v[2:3], v[0:1], v[90:91] op_sel_hi:[0,1]
	v_pk_mul_f32 v[2:3], v[44:45], v[2:3]
	v_mov_b32_e32 v8, v1
	v_cvt_pk_bf16_f32 v118, v2, v3
	v_pk_mul_f32 v[2:3], v[0:1], v[88:89] op_sel_hi:[0,1]
	v_pk_mul_f32 v[2:3], v[46:47], v[2:3]
	v_mov_b32_e32 v9, v1
	v_cvt_pk_bf16_f32 v119, v2, v3
	v_pk_mul_f32 v[2:3], v[0:1], v[86:87] op_sel_hi:[0,1]
	v_pk_mul_f32 v[2:3], v[14:15], v[2:3]
	v_mov_b32_e32 v14, v1
	v_cvt_pk_bf16_f32 v120, v2, v3
	v_pk_mul_f32 v[2:3], v[0:1], v[84:85] op_sel_hi:[0,1]
	v_pk_mul_f32 v[2:3], v[16:17], v[2:3]
	v_mov_b32_e32 v15, v1
	v_cvt_pk_bf16_f32 v121, v2, v3
	v_pk_mul_f32 v[2:3], v[0:1], v[82:83] op_sel_hi:[0,1]
	v_pk_mul_f32 v[2:3], v[40:41], v[2:3]
	v_mov_b32_e32 v10, v1
	v_cvt_pk_bf16_f32 v122, v2, v3
	v_pk_mul_f32 v[2:3], v[0:1], v[80:81] op_sel_hi:[0,1]
	v_pk_mul_f32 v[2:3], v[42:43], v[2:3]
	v_mov_b32_e32 v11, v1
	v_cvt_pk_bf16_f32 v123, v2, v3
	v_pk_mul_f32 v[2:3], v[0:1], v[78:79] op_sel_hi:[0,1]
	v_pk_mul_f32 v[2:3], v[36:37], v[2:3]
	v_mov_b32_e32 v12, v1
	v_cvt_pk_bf16_f32 v124, v2, v3
	v_pk_mul_f32 v[2:3], v[0:1], v[76:77] op_sel_hi:[0,1]
	v_pk_mul_f32 v[2:3], v[38:39], v[2:3]
	v_mov_b32_e32 v13, v1
	v_cvt_pk_bf16_f32 v125, v2, v3
	v_pk_mul_f32 v[2:3], v[74:75], v[0:1] op_sel_hi:[1,0]
	v_mul_u32_u24_e32 v237, 0x90, v59
	v_pk_mul_f32 v[2:3], v[32:33], v[2:3]
	v_add_u32_e32 v239, v58, v139
	v_cvt_pk_bf16_f32 v126, v2, v3
	v_pk_mul_f32 v[2:3], v[72:73], v[0:1] op_sel_hi:[1,0]
	s_mov_b32 s13, 0
	v_pk_mul_f32 v[2:3], v[34:35], v[2:3]
	v_mov_b32_e32 v250, 0
	v_cvt_pk_bf16_f32 v127, v2, v3
	v_pk_mul_f32 v[2:3], v[70:71], v[0:1] op_sel_hi:[1,0]
	v_mov_b32_e32 v249, 0
	v_pk_mul_f32 v[2:3], v[18:19], v[2:3]
	s_nop 0
	v_cvt_pk_bf16_f32 v128, v2, v3
	v_pk_mul_f32 v[2:3], v[68:69], v[0:1] op_sel_hi:[1,0]
	s_nop 0
	v_pk_mul_f32 v[2:3], v[20:21], v[2:3]
	s_nop 0
	v_cvt_pk_bf16_f32 v129, v2, v3
	v_pk_mul_f32 v[2:3], v[22:23], v[0:1] op_sel_hi:[1,0]
	s_nop 0
	v_pk_mul_f32 v[2:3], v[28:29], v[2:3]
	s_nop 0
	v_cvt_pk_bf16_f32 v130, v2, v3
	v_pk_mul_f32 v[2:3], v[64:65], v[0:1] op_sel_hi:[1,0]
	s_nop 0
	v_pk_mul_f32 v[2:3], v[30:31], v[2:3]
	s_nop 0
	v_cvt_pk_bf16_f32 v131, v2, v3
	v_pk_mul_f32 v[2:3], v[62:63], v[0:1] op_sel_hi:[1,0]
	s_nop 0
	v_pk_mul_f32 v[2:3], v[24:25], v[2:3]
	s_nop 0
	v_cvt_pk_bf16_f32 v132, v2, v3
	v_pk_mul_f32 v[2:3], v[60:61], v[0:1] op_sel_hi:[1,0]
	v_and_b32_e32 v0, 19, v136
	v_pk_mul_f32 v[2:3], v[2:3], v[26:27]
	s_nop 0
	v_cvt_pk_bf16_f32 v133, v2, v3
	v_lshlrev_b32_e32 v2, 1, v136
	v_lshrrev_b32_e32 v3, 1, v136
	v_and_b32_e32 v2, 8, v2
	v_and_b32_e32 v3, 4, v3
	v_or3_b32 v0, v0, v2, v3
	v_mul_u32_u24_e32 v233, 0xd0, v0
	v_add_u32_e32 v0, s46, v138
	v_lshlrev_b64 v[2:3], 9, v[0:1]
	v_lshl_or_b32 v2, v137, 4, v2
	v_lshl_add_u64 v[240:241], s[38:39], 0, v[2:3]
	v_lshl_add_u64 v[2:3], s[46:47], 0, v[56:57]
	v_lshlrev_b64 v[2:3], 10, v[2:3]
	v_lshl_or_b32 v2, v135, 4, v2
	v_lshl_add_u32 v0, v135, 13, s8
	v_lshl_add_u64 v[242:243], s[42:43], 0, v[2:3]
	v_and_b32_e32 v0, 0xffff0000, v0
	v_lshlrev_b64 v[2:3], 7, v[56:57]
	v_lshl_add_u64 v[2:3], v[0:1], 0, v[2:3]
	v_add_lshl_u32 v0, s46, v134, 1
	v_and_or_b32 v2, v0, s12, v2
	v_lshl_add_u64 v[244:245], s[44:45], 0, v[2:3]
	v_mov_b32_e32 v0, v1
	v_mov_b32_e32 v2, v1
	v_mov_b32_e32 v3, v1
	v_mov_b64_e32 v[32:33], v[14:15]
	v_mov_b64_e32 v[30:31], v[12:13]
	v_mov_b64_e32 v[28:29], v[10:11]
	v_mov_b64_e32 v[26:27], v[8:9]
	v_mov_b64_e32 v[24:25], v[6:7]
	v_mov_b64_e32 v[22:23], v[4:5]
	v_mov_b64_e32 v[20:21], v[2:3]
	v_mov_b64_e32 v[18:19], v[0:1]
	v_mov_b64_e32 v[16:17], v[14:15]
	v_mov_b64_e32 v[14:15], v[12:13]
	v_mov_b64_e32 v[12:13], v[10:11]
	v_mov_b64_e32 v[10:11], v[8:9]
	v_mov_b64_e32 v[8:9], v[6:7]
	v_mov_b64_e32 v[6:7], v[4:5]
	v_mov_b64_e32 v[4:5], v[2:3]
	v_mov_b64_e32 v[2:3], v[0:1]
	v_mov_b32_e32 v212, 0xff800000
	v_mov_b32_e32 v213, 0xff800000
	v_mov_b32_e32 v34, 0
	v_mov_b32_e32 v35, 0
	v_mov_b32_e32 v36, 0
	v_mov_b32_e32 v37, 0
	v_mov_b32_e32 v38, 0
	v_mov_b32_e32 v39, 0
	v_mov_b32_e32 v40, 0
	v_mov_b32_e32 v41, 0
	v_mov_b32_e32 v42, 0
	v_mov_b32_e32 v43, 0
	v_mov_b32_e32 v44, 0
	v_mov_b32_e32 v45, 0
	v_mov_b32_e32 v46, 0
	v_mov_b32_e32 v47, 0
	v_mov_b32_e32 v48, 0
	v_mov_b32_e32 v49, 0
	s_cmp_gt_i32 s5, 1
	s_cbranch_scc0 .Latt_nold_pre
	global_load_dwordx4 v[98:101], v[242:243], off
	global_load_dwordx4 v[102:105], v[244:245], off
	s_and_saveexec_b64 s[50:51], s[40:41]
	s_cbranch_execz .Latt_ldx_pre
	global_load_dwordx4 v[106:109], v[240:241], off
; #define LAS __attribute__((address_space(3)))
; __device__ __forceinline__ void attn_item(const Params& p, int l, LAS unsigned char* lds, int b, int h, int J) {
;     ...
; #pragma nounroll
;     for (int j = 0; j < blk_nt; ++j) {
;         LAS unsigned char* cur = lds + (j & 1) * ATT_BUF; LAS unsigned char* nxt = lds + ((j + 1) & 1) * ATT_BUF;
;         const bool more = (j + 1) < blk_nt;
;         if (more) { skn = *(const u32x4*)(gkn + (size_t)(j + 1) * 64 * 512); svt = *(const u32x4*)(gvt + (size_t)(j + 1) * 512 * 64); if (has_kr) skr = *(const u32x4*)(gkr + (size_t)(j + 1) * 64 * 256); }
;         if (j < my_nt) {
;             bf16x8 ka[2][6], va[2][4];
; #pragma unroll
;             for (int kb = 0; kb < 2; ++kb)
; #pragma unroll
;                 for (int s = 0; s < 6; ++s) ka[kb][s] = *(const LAS bf16x8*)(cur + rk + kb * 32 * KROW + 32 * s);
; #pragma unroll
;             for (int dvb = 0; dvb < 2; ++dvb)
; #pragma unroll
;                 for (int ks = 0; ks < 4; ++ks) va[dvb][ks] = *(const LAS bf16x8*)(cur + rv + dvb * 32 * VROW + 32 * ks);
;             __builtin_amdgcn_sched_barrier(0);
;             if (j < my_nt - 1) attn_step<false>(ka, va, qf, 64, lane, o0, o1, mrun, lsum); else attn_step<true>(ka, va, qf, 16, lane, o0, o1, mrun, lsum);
;         }
;         if (more) { *(LAS u32x4*)(nxt + wkn) = skn; *(LAS u32x4*)(nxt + wvt) = svt; if (has_kr) *(LAS u32x4*)(nxt + wkr) = skr; }
.Latt_ldx_pre:
	s_or_b64 exec, exec, s[50:51]
	s_mov_b64 s[14:15], 0x8000
	v_lshl_add_u64 v[240:241], v[240:241], 0, s[14:15]
	v_lshl_add_u64 v[242:243], v[242:243], 0, s[34:35]
	v_lshl_add_u64 v[244:245], v[244:245], 0, s[34:35]
.Latt_nold_pre:
	s_cmp_eq_u64 s[40:41], 0
	s_cbranch_scc0 .Latt_head
	s_barrier
.Latt_head:
	s_add_i32 s12, s13, 1
	s_cmp_lt_i32 s12, s5
	s_cbranch_scc0 .Latt_noe
	s_bitcmp1_b32 s12, 0
	s_cselect_b32 s14, 0x5800, 0
	v_add_u32_e32 v0, s14, v234
	s_waitcnt vmcnt(1)
	ds_write_b128 v0, v[98:101]
	v_add_u32_e32 v0, s14, v238
	s_waitcnt vmcnt(0)
	ds_write_b128 v0, v[102:105] offset:13312
	s_and_saveexec_b64 s[50:51], s[40:41]
	v_add_u32_e32 v0, s14, v239
	ds_write_b128 v0, v[106:109] offset:128
	s_or_b64 exec, exec, s[50:51]
.Latt_noe:
	s_cmp_ge_i32 s13, s11
	s_cbranch_scc1 .Latt_skip
	s_bitcmp1_b32 s13, 0
	s_cselect_b32 s14, 0x5800, 0
	s_add_i32 s14, s14, 0
	v_add3_u32 v0, s14, v233, v236
	ds_read_b128 v[186:189], v0
	ds_read_b128 v[182:185], v0 offset:32
	ds_read_b128 v[178:181], v0 offset:64
	ds_read_b128 v[174:177], v0 offset:96
	ds_read_b128 v[170:173], v0 offset:128
	ds_read_b128 v[166:169], v0 offset:160
	ds_read_b128 v[50:53], v0 offset:6656
	ds_read_b128 v[206:209], v0 offset:6688
	ds_read_b128 v[202:205], v0 offset:6720
	ds_read_b128 v[198:201], v0 offset:6752
	ds_read_b128 v[194:197], v0 offset:6784
	ds_read_b128 v[190:193], v0 offset:6816
	v_add3_u32 v0, s14, v237, v236
	ds_read_b128 v[158:161], v0 offset:13312
	ds_read_b128 v[150:153], v0 offset:13344
	ds_read_b128 v[146:149], v0 offset:13376
	ds_read_b128 v[138:141], v0 offset:13408
	ds_read_b128 v[162:165], v0 offset:17920
	ds_read_b128 v[154:157], v0 offset:17952
	ds_read_b128 v[142:145], v0 offset:17984
	ds_read_b128 v[134:137], v0 offset:18016
	s_cmp_gt_i32 s13, s10
	s_cbranch_scc1 .Latt_masked
	s_waitcnt lgkmcnt(14)
	v_mfma_f32_32x32x16_bf16 v[66:81], v[186:189], v[110:113], v[34:49]
	v_mfma_f32_32x32x16_bf16 v[66:81], v[182:185], v[114:117], v[66:81]
	s_waitcnt lgkmcnt(13)
	v_mfma_f32_32x32x16_bf16 v[50:65], v[50:53], v[110:113], v[34:49]
	v_mfma_f32_32x32x16_bf16 v[66:81], v[178:181], v[118:121], v[66:81]
	s_waitcnt lgkmcnt(12)
	v_mfma_f32_32x32x16_bf16 v[50:65], v[206:209], v[114:117], v[50:65]
	v_mfma_f32_32x32x16_bf16 v[66:81], v[174:177], v[122:125], v[66:81]
	s_waitcnt lgkmcnt(11)
	v_mfma_f32_32x32x16_bf16 v[50:65], v[202:205], v[118:121], v[50:65]
	v_mfma_f32_32x32x16_bf16 v[66:81], v[170:173], v[126:129], v[66:81]
	s_waitcnt lgkmcnt(10)
	v_mfma_f32_32x32x16_bf16 v[50:65], v[198:201], v[122:125], v[50:65]
	v_mfma_f32_32x32x16_bf16 v[66:81], v[166:169], v[130:133], v[66:81]
	s_waitcnt lgkmcnt(9)
	v_mfma_f32_32x32x16_bf16 v[50:65], v[194:197], v[126:129], v[50:65]
	s_nop 9
	v_max3_f32 v0, v66, v67, v68
	v_max3_f32 v0, v0, v69, v70
	v_max3_f32 v0, v0, v71, v72
	v_max3_f32 v0, v0, v73, v74
	v_max3_f32 v0, v0, v75, v76
	s_waitcnt lgkmcnt(8)
	v_mfma_f32_32x32x16_bf16 v[50:65], v[190:193], v[130:133], v[50:65]
	v_max3_f32 v0, v0, v77, v78
	v_max3_f32 v0, v0, v79, v80
	v_max_f32_e32 v0, v0, v81
	s_nop 8
	v_max3_f32 v0, v0, v50, v51
	v_max3_f32 v0, v0, v52, v53
	v_max3_f32 v0, v0, v54, v55
	v_max3_f32 v0, v0, v56, v57
	v_max3_f32 v0, v0, v58, v59
	v_max3_f32 v0, v0, v60, v61
	v_max3_f32 v0, v0, v62, v63
	v_max3_f32 v0, v0, v64, v65
	s_waitcnt lgkmcnt(0)
	s_barrier
	s_add_i32 s14, s12, 1
	s_cmp_lt_i32 s14, s5
	s_cbranch_scc0 .Latt_nold_main
	global_load_dwordx4 v[98:101], v[242:243], off
	global_load_dwordx4 v[102:105], v[244:245], off
	s_and_saveexec_b64 s[50:51], s[40:41]
	s_cbranch_execz .Latt_ldx_main
	global_load_dwordx4 v[106:109], v[240:241], off

; __device__ __forceinline__ float shx32(float v, int lane) { return __int_as_float(__builtin_amdgcn_ds_bpermute((lane ^ 32) << 2, __float_as_int(v))); }
; template <bool MASKED>
; __device__ __forceinline__ void attn_step(const bf16x8 (&ka)[2][6], const bf16x8 (&va)[2][4], const bf16x8 (&qf)[6], int nvalid, int lane, f32x16& o0, f32x16& o1, float& mrun, float& lsum) {
;     ...
;     if (__builtin_amdgcn_ballot_w64(mx > mrun + 8.0f) != 0ull) {
;         mx = fmaxf(mx, shx32(mx, lane));
;         const float mnew = fmaxf(mrun, mx);
;         const float alpha = __builtin_amdgcn_exp2f(mrun - mnew);
;         mrun = mnew; lsum *= alpha;
; #pragma unroll
;         for (int i = 0; i < 16; ++i) { o0[i] *= alpha; o1[i] *= alpha; }
;     }
.Latt_nold_main:
	v_cmp_gt_f32_e32 vcc, v0, v212
	s_cbranch_vccz .Latt_softmax
	ds_bpermute_b32 v82, v235, v0
	s_waitcnt lgkmcnt(0)
	v_max3_f32 v82, v0, v82, v213
	v_exp_f32_e64 v84, -v82
	v_add_f32_e32 v250, v250, v82
	v_mov_b32_e32 v212, 0x41000000
	v_mul_f32_e32 v249, v249, v84
	v_pk_mul_f32 v[32:33], v[32:33], v[84:85] op_sel_hi:[1,0]
	v_pk_mul_f32 v[30:31], v[30:31], v[84:85] op_sel_hi:[1,0]
	v_pk_mul_f32 v[28:29], v[28:29], v[84:85] op_sel_hi:[1,0]
	v_pk_mul_f32 v[26:27], v[26:27], v[84:85] op_sel_hi:[1,0]
	v_pk_mul_f32 v[24:25], v[24:25], v[84:85] op_sel_hi:[1,0]
	v_pk_mul_f32 v[22:23], v[22:23], v[84:85] op_sel_hi:[1,0]
	v_pk_mul_f32 v[20:21], v[20:21], v[84:85] op_sel_hi:[1,0]
	v_pk_mul_f32 v[18:19], v[18:19], v[84:85] op_sel_hi:[1,0]
	v_pk_mul_f32 v[16:17], v[16:17], v[84:85] op_sel_hi:[1,0]
	v_pk_mul_f32 v[14:15], v[14:15], v[84:85] op_sel_hi:[1,0]
	v_pk_mul_f32 v[12:13], v[12:13], v[84:85] op_sel_hi:[1,0]
	v_pk_mul_f32 v[10:11], v[10:11], v[84:85] op_sel_hi:[1,0]
	v_pk_mul_f32 v[8:9], v[8:9], v[84:85] op_sel_hi:[1,0]
	v_pk_mul_f32 v[6:7], v[6:7], v[84:85] op_sel_hi:[1,0]
	v_pk_mul_f32 v[4:5], v[4:5], v[84:85] op_sel_hi:[1,0]
	v_pk_mul_f32 v[2:3], v[2:3], v[84:85] op_sel_hi:[1,0]
	v_mov_b32_e32 v213, 0
	v_xor_b32_e32 v34, 0x80000000, v250
	v_sub_f32_e32 v66, v66, v82
	v_sub_f32_e32 v67, v67, v82
	v_sub_f32_e32 v68, v68, v82
	v_sub_f32_e32 v69, v69, v82
	v_sub_f32_e32 v70, v70, v82
	v_sub_f32_e32 v71, v71, v82
	v_sub_f32_e32 v72, v72, v82
	v_sub_f32_e32 v73, v73, v82
	v_sub_f32_e32 v74, v74, v82
	v_sub_f32_e32 v75, v75, v82
	v_sub_f32_e32 v76, v76, v82
	v_sub_f32_e32 v77, v77, v82
	v_sub_f32_e32 v78, v78, v82
	v_sub_f32_e32 v79, v79, v82
	v_sub_f32_e32 v80, v80, v82
	v_sub_f32_e32 v81, v81, v82
	v_sub_f32_e32 v50, v50, v82
	v_sub_f32_e32 v51, v51, v82
	v_sub_f32_e32 v52, v52, v82
	v_sub_f32_e32 v53, v53, v82
	v_sub_f32_e32 v54, v54, v82
	v_sub_f32_e32 v55, v55, v82
	v_sub_f32_e32 v56, v56, v82
	v_sub_f32_e32 v57, v57, v82
	v_sub_f32_e32 v58, v58, v82
	v_sub_f32_e32 v59, v59, v82
	v_sub_f32_e32 v60, v60, v82
	v_sub_f32_e32 v61, v61, v82
	v_sub_f32_e32 v62, v62, v82
	v_sub_f32_e32 v63, v63, v82
	v_sub_f32_e32 v64, v64, v82
	v_sub_f32_e32 v65, v65, v82
	v_mov_b32_e32 v35, v34
	v_mov_b32_e32 v36, v34
	v_mov_b32_e32 v37, v34
	v_mov_b32_e32 v38, v34
	v_mov_b32_e32 v39, v34
	v_mov_b32_e32 v40, v34
	v_mov_b32_e32 v41, v34
	v_mov_b32_e32 v42, v34
	v_mov_b32_e32 v43, v34
	v_mov_b32_e32 v44, v34
	v_mov_b32_e32 v45, v34
	v_mov_b32_e32 v46, v34
	v_mov_b32_e32 v47, v34
	v_mov_b32_e32 v48, v34
	v_mov_b32_e32 v49, v34

; __device__ __forceinline__ void attn_item(const Params& p, int l, LAS unsigned char* lds, int b, int h, int J) {
;     ...
;         if (more) { skn = *(const u32x4*)(gkn + (size_t)(j + 1) * 64 * 512); svt = *(const u32x4*)(gvt + (size_t)(j + 1) * 512 * 64); if (has_kr) skr = *(const u32x4*)(gkr + (size_t)(j + 1) * 64 * 256); }
;     ...
;             if (j < my_nt - 1) attn_step<false>(ka, va, qf, 64, lane, o0, o1, mrun, lsum); else attn_step<true>(ka, va, qf, 16, lane, o0, o1, mrun, lsum);
.Latt_masked:
	v_add_f32_e32 v212, 0x41000000, v250
	s_waitcnt lgkmcnt(0)
	s_barrier
	s_add_i32 s14, s12, 1
	s_cmp_lt_i32 s14, s5
	s_cbranch_scc0 .Latt_nold_mask
	global_load_dwordx4 v[98:101], v[242:243], off
	global_load_dwordx4 v[102:105], v[244:245], off
	s_and_saveexec_b64 s[50:51], s[40:41]
	s_cbranch_execz .Latt_ldx_mask
	global_load_dwordx4 v[106:109], v[240:241], off

; __device__ __forceinline__ float shx32(float v, int lane) { return __int_as_float(__builtin_amdgcn_ds_bpermute((lane ^ 32) << 2, __float_as_int(v))); }
; template <bool MASKED>
; __device__ __forceinline__ void attn_step(const bf16x8 (&ka)[2][6], const bf16x8 (&va)[2][4], const bf16x8 (&qf)[6], int nvalid, int lane, f32x16& o0, f32x16& o1, float& mrun, float& lsum) {
;     ...
;     for (int s = 0; s < 6; ++s) { s0 = __builtin_amdgcn_mfma_f32_32x32x16_bf16(ka[0][s], qf[s], s0, 0, 0, 0); s1 = __builtin_amdgcn_mfma_f32_32x32x16_bf16(ka[1][s], qf[s], s1, 0, 0, 0); }
;     if (MASKED) {
; #pragma unroll
;         for (int i = 0; i < 16; ++i) { if (16 * (i >> 3) >= nvalid) s0[i] = -INFINITY; if (32 + 16 * (i >> 3) >= nvalid) s1[i] = -INFINITY; }
;     }
;     float mx = fmaxf(fmaxf(s0[0], s0[1]), s0[2]);
; #pragma unroll
;     for (int i = 3; i < 15; i += 2) mx = fmaxf(fmaxf(mx, s0[i]), s0[i + 1]);
;     mx = fmaxf(mx, s0[15]);
; #pragma unroll
;     for (int i = 0; i < 16; i += 2) mx = fmaxf(fmaxf(mx, s1[i]), s1[i + 1]);
;     if (__builtin_amdgcn_ballot_w64(mx > mrun + 8.0f) != 0ull) {
;         mx = fmaxf(mx, shx32(mx, lane));
;         const float mnew = fmaxf(mrun, mx);
;         const float alpha = __builtin_amdgcn_exp2f(mrun - mnew);
;         mrun = mnew; lsum *= alpha;
; #pragma unroll
;         for (int i = 0; i < 16; ++i) { o0[i] *= alpha; o1[i] *= alpha; }
;     }
.Latt_nold_mask:
	v_mov_b64_e32 v[200:201], v[216:217]
	v_mfma_f32_32x32x16_bf16 v[34:49], v[186:189], v[110:113], 0
	v_mfma_f32_32x32x16_bf16 v[34:49], v[182:185], v[114:117], v[34:49]
	v_mfma_f32_32x32x16_bf16 v[34:49], v[178:181], v[118:121], v[34:49]
	v_mfma_f32_32x32x16_bf16 v[34:49], v[174:177], v[122:125], v[34:49]
	v_mfma_f32_32x32x16_bf16 v[34:49], v[170:173], v[126:129], v[34:49]
	v_mfma_f32_32x32x16_bf16 v[34:49], v[166:169], v[130:133], v[34:49]
	s_nop 11
	v_max3_f32 v0, v34, v35, v36
	v_max3_f32 v0, v0, v37, v38
	v_max3_f32 v0, v0, v39, v40
	v_max3_f32 v0, v0, v41, s59
	v_cmp_gt_f32_e32 vcc, v0, v212
	s_cbranch_vccz .LBB0_628
	ds_bpermute_b32 v42, v235, v0
	s_waitcnt lgkmcnt(0)
	v_max3_f32 v0, v250, v0, v42
	v_sub_f32_e32 v42, v250, v0
	v_exp_f32_e32 v42, v42
	v_mov_b32_e32 v250, v0
	v_mul_f32_e32 v249, v249, v42
	v_pk_mul_f32 v[32:33], v[32:33], v[42:43] op_sel_hi:[1,0]
	v_pk_mul_f32 v[30:31], v[30:31], v[42:43] op_sel_hi:[1,0]
	v_pk_mul_f32 v[28:29], v[28:29], v[42:43] op_sel_hi:[1,0]
	v_pk_mul_f32 v[26:27], v[26:27], v[42:43] op_sel_hi:[1,0]
	v_pk_mul_f32 v[24:25], v[24:25], v[42:43] op_sel_hi:[1,0]
	v_pk_mul_f32 v[22:23], v[22:23], v[42:43] op_sel_hi:[1,0]
	v_pk_mul_f32 v[20:21], v[20:21], v[42:43] op_sel_hi:[1,0]
	v_pk_mul_f32 v[18:19], v[18:19], v[42:43] op_sel_hi:[1,0]
	v_pk_mul_f32 v[16:17], v[16:17], v[42:43] op_sel_hi:[1,0]
	v_pk_mul_f32 v[14:15], v[14:15], v[42:43] op_sel_hi:[1,0]
	v_pk_mul_f32 v[12:13], v[12:13], v[42:43] op_sel_hi:[1,0]
	v_pk_mul_f32 v[10:11], v[10:11], v[42:43] op_sel_hi:[1,0]
	v_pk_mul_f32 v[8:9], v[8:9], v[42:43] op_sel_hi:[1,0]
	v_pk_mul_f32 v[6:7], v[6:7], v[42:43] op_sel_hi:[1,0]
	v_pk_mul_f32 v[4:5], v[4:5], v[42:43] op_sel_hi:[1,0]
	v_pk_mul_f32 v[2:3], v[2:3], v[42:43] op_sel_hi:[1,0]
	s_branch .LBB0_629

; #define LAS __attribute__((address_space(3)))
; __device__ __forceinline__ void attn_item(const Params& p, int l, LAS unsigned char* lds, int b, int h, int J) {
;     ...
;         if (more) { skn = *(const u32x4*)(gkn + (size_t)(j + 1) * 64 * 512); svt = *(const u32x4*)(gvt + (size_t)(j + 1) * 512 * 64); if (has_kr) skr = *(const u32x4*)(gkr + (size_t)(j + 1) * 64 * 256); }
;         if (j < my_nt) {
;     ...
;         if (more) { *(LAS u32x4*)(nxt + wkn) = skn; *(LAS u32x4*)(nxt + wvt) = svt; if (has_kr) *(LAS u32x4*)(nxt + wkr) = skr; }
;         __syncthreads();
.Latt_skip:
	s_waitcnt lgkmcnt(0)
	s_barrier
	s_add_i32 s14, s12, 1
	s_cmp_lt_i32 s14, s5
	s_cbranch_scc0 .Latt_nold_skip
	global_load_dwordx4 v[98:101], v[242:243], off
	global_load_dwordx4 v[102:105], v[244:245], off
	s_and_saveexec_b64 s[50:51], s[40:41]
	s_cbranch_execz .Latt_ldx_skip
	global_load_dwordx4 v[106:109], v[240:241], off

; __device__ __forceinline__ void attn_item(const Params& p, int l, LAS unsigned char* lds, int b, int h, int J) {
;     ...
;     for (int j = 0; j < blk_nt; ++j) {
;     ...
;         __syncthreads();
;     }
.Latt_nold_skip:
.Latt_end:
	s_cmp_lg_u32 s5, s12
	s_waitcnt lgkmcnt(0)
	s_barrier
	s_cbranch_scc0 .Latt_exit
	s_mov_b32 s13, s12
	s_branch .Latt_head
